# M12 + absmax_tile W-row loads de-serialised (P0)
# speedup vs baseline: 1.0107x; 1.0039x over previous
.LBB0_75:
	s_and_b32 s4, s1, 0x3f80
	s_and_b32 s12, s3, 0x780
	s_addk_i32 s4, 0xec00
	v_lshl_add_u64 v[14:15], s[4:5], 2, v[10:11]
	v_add_u32_e32 v120, s12, v37
	v_ashrrev_i32_e32 v121, 31, v120
	v_mad_i64_i32 v[122:123], s[40:41], v120, s68, v[14:15]
	v_lshl_add_u64 v[124:125], v[120:121], 2, s[50:51]
	global_load_dwordx4 v[68:71], v[122:123], off nt
	global_load_dword v100, v[124:125], off
	v_add_u32_e32 v120, s12, v7
	v_ashrrev_i32_e32 v121, 31, v120
	v_mad_i64_i32 v[122:123], s[40:41], v120, s68, v[14:15]
	v_lshl_add_u64 v[124:125], v[120:121], 2, s[50:51]
	global_load_dwordx4 v[72:75], v[122:123], off nt
	global_load_dword v102, v[124:125], off
	v_add_u32_e32 v120, s12, v9
	v_ashrrev_i32_e32 v121, 31, v120
	v_mad_i64_i32 v[122:123], s[40:41], v120, s68, v[14:15]
	v_lshl_add_u64 v[124:125], v[120:121], 2, s[50:51]
	global_load_dwordx4 v[76:79], v[122:123], off nt
	global_load_dword v104, v[124:125], off
	v_add_u32_e32 v120, s12, v18
	v_ashrrev_i32_e32 v121, 31, v120
	v_mad_i64_i32 v[122:123], s[40:41], v120, s68, v[14:15]
	v_lshl_add_u64 v[124:125], v[120:121], 2, s[50:51]
	global_load_dwordx4 v[80:83], v[122:123], off nt
	global_load_dword v106, v[124:125], off
	v_add_u32_e32 v120, s12, v19
	v_ashrrev_i32_e32 v121, 31, v120
	v_mad_i64_i32 v[122:123], s[40:41], v120, s68, v[14:15]
	v_lshl_add_u64 v[124:125], v[120:121], 2, s[50:51]
	global_load_dwordx4 v[84:87], v[122:123], off nt
	global_load_dword v108, v[124:125], off
	v_add_u32_e32 v120, s12, v20
	v_ashrrev_i32_e32 v121, 31, v120
	v_mad_i64_i32 v[122:123], s[40:41], v120, s68, v[14:15]
	v_lshl_add_u64 v[124:125], v[120:121], 2, s[50:51]
	global_load_dwordx4 v[88:91], v[122:123], off nt
	global_load_dword v110, v[124:125], off
	v_add_u32_e32 v120, s12, v21
	v_ashrrev_i32_e32 v121, 31, v120
	v_mad_i64_i32 v[122:123], s[40:41], v120, s68, v[14:15]
	v_lshl_add_u64 v[124:125], v[120:121], 2, s[50:51]
	global_load_dwordx4 v[92:95], v[122:123], off nt
	global_load_dword v112, v[124:125], off
	v_add_u32_e32 v120, s12, v22
	v_ashrrev_i32_e32 v121, 31, v120
	v_mad_i64_i32 v[122:123], s[40:41], v120, s68, v[14:15]
	v_lshl_add_u64 v[124:125], v[120:121], 2, s[50:51]
	global_load_dwordx4 v[96:99], v[122:123], off nt
	global_load_dword v118, v[124:125], off
	s_waitcnt vmcnt(14)
	v_pk_mul_f32 v[40:41], v[70:71], v[100:101] op_sel_hi:[1,0]
	v_pk_mul_f32 v[16:17], v[68:69], v[100:101] op_sel_hi:[1,0]
	s_nop 0
	s_waitcnt vmcnt(12)
	v_pk_mul_f32 v[2:3], v[72:73], v[102:103] op_sel_hi:[1,0]
	s_nop 0
	v_max3_f32 v44, |v16|, 0, |v2|
	v_max3_f32 v45, |v17|, 0, |v3|
	v_pk_mul_f32 v[4:5], v[74:75], v[102:103] op_sel_hi:[1,0]
	v_max3_f32 v46, |v40|, 0, |v4|
	v_max3_f32 v47, |v41|, 0, |v5|
	s_waitcnt vmcnt(10)
	v_pk_mul_f32 v[40:41], v[78:79], v[104:105] op_sel_hi:[1,0]
	v_pk_mul_f32 v[16:17], v[76:77], v[104:105] op_sel_hi:[1,0]
	s_nop 0
	s_waitcnt vmcnt(8)
	v_pk_mul_f32 v[2:3], v[80:81], v[106:107] op_sel_hi:[1,0]
	s_nop 0
	v_max3_f32 v44, v44, |v16|, |v2|
	v_max3_f32 v45, v45, |v17|, |v3|
	v_pk_mul_f32 v[4:5], v[82:83], v[106:107] op_sel_hi:[1,0]
	v_max3_f32 v46, v46, |v40|, |v4|
	v_max3_f32 v47, v47, |v41|, |v5|
	s_waitcnt vmcnt(6)
	v_pk_mul_f32 v[40:41], v[86:87], v[108:109] op_sel_hi:[1,0]
	v_pk_mul_f32 v[16:17], v[84:85], v[108:109] op_sel_hi:[1,0]
	s_nop 0
	s_waitcnt vmcnt(4)
	v_pk_mul_f32 v[2:3], v[88:89], v[110:111] op_sel_hi:[1,0]
	s_nop 0
	v_max3_f32 v44, v44, |v16|, |v2|
	v_max3_f32 v45, v45, |v17|, |v3|
	v_pk_mul_f32 v[4:5], v[90:91], v[110:111] op_sel_hi:[1,0]
	v_max3_f32 v46, v46, |v40|, |v4|
	v_max3_f32 v47, v47, |v41|, |v5|
	s_waitcnt vmcnt(2)
	v_pk_mul_f32 v[40:41], v[94:95], v[112:113] op_sel_hi:[1,0]
	v_pk_mul_f32 v[16:17], v[92:93], v[112:113] op_sel_hi:[1,0]
	s_nop 0
	s_waitcnt vmcnt(0)
	v_pk_mul_f32 v[4:5], v[98:99], v[118:119] op_sel_hi:[1,0]
	v_pk_mul_f32 v[2:3], v[96:97], v[118:119] op_sel_hi:[1,0]
	v_max3_f32 v4, v46, |v40|, |v4|
	v_max3_f32 v2, v44, |v16|, |v2|
	v_max3_f32 v3, v45, |v17|, |v3|
	v_max3_f32 v5, v47, |v41|, |v5|
	ds_write_b128 v23, v[2:5]
	s_waitcnt lgkmcnt(0)
	s_barrier
	s_and_saveexec_b64 s[12:13], s[36:37]
	s_cbranch_execz .LBB0_77
	ds_read2st64_b32 v[2:3], v24 offset1:2
	s_waitcnt lgkmcnt(0)
	v_max_f32_e32 v3, v3, v3
	v_max_f32_e32 v2, v2, v2
	v_max_f32_e32 v4, v2, v3
	ds_read2st64_b32 v[2:3], v24 offset0:4 offset1:6
	s_waitcnt lgkmcnt(0)
	v_max3_f32 v4, v4, v2, v3
	ds_read2st64_b32 v[2:3], v24 offset0:8 offset1:10
	s_waitcnt lgkmcnt(0)
	v_max3_f32 v4, v4, v2, v3
	ds_read2st64_b32 v[2:3], v24 offset0:12 offset1:14
	s_waitcnt lgkmcnt(0)
	v_max3_f32 v4, v4, v2, v3
	ds_read2st64_b32 v[2:3], v24 offset0:16 offset1:18
	s_waitcnt lgkmcnt(0)
	v_max3_f32 v4, v4, v2, v3
	ds_read2st64_b32 v[2:3], v24 offset0:20 offset1:22
	s_waitcnt lgkmcnt(0)
	v_max3_f32 v4, v4, v2, v3
	ds_read2st64_b32 v[2:3], v24 offset0:24 offset1:26
	s_waitcnt lgkmcnt(0)
	v_max3_f32 v4, v4, v2, v3
	ds_read2st64_b32 v[2:3], v24 offset0:28 offset1:30
	s_waitcnt lgkmcnt(0)
	v_max3_f32 v4, v4, v2, v3
	v_lshl_add_u64 v[2:3], s[4:5], 2, v[12:13]
	global_atomic_umax v[2:3], v4, off
